# grid barrier: XCD leader releases its local workgroups before its own L1 invalidate
# speedup vs baseline: 1.0203x; 1.0027x over previous
; __device__ __forceinline__ unsigned xb_add(unsigned* p, unsigned v) { return __hip_atomic_fetch_add(p, v, __ATOMIC_RELAXED, __HIP_MEMORY_SCOPE_AGENT); }
; __device__ __forceinline__ void grid_barrier(unsigned* bar, unsigned G, int tid, volatile LAS unsigned* st) {
;     ...
;             __builtin_amdgcn_fence(__ATOMIC_ACQUIRE, "agent");
;             xb_add(&bar[XB_XGEN(x)], 1u);
;             asm volatile("s_waitcnt vmcnt(0)" ::: "memory");
.LBB0_166:
	s_or_b64 exec, exec, s[4:5]
	s_mov_b64 s[4:5], exec
	v_mbcnt_lo_u32_b32 v0, s4, 0
	v_mbcnt_hi_u32_b32 v0, s5, v0
	v_cmp_eq_u32_e32 vcc, 0, v0
	s_waitcnt vmcnt(0)
	s_and_saveexec_b64 s[6:7], vcc
	s_cbranch_execz .LBB0_168
	s_bcnt1_i32_b64 s4, s[4:5]
	v_mov_b32_e32 v0, 0x2000
	v_mov_b32_e32 v1, s4
	global_atomic_add v0, v1, s[2:3] offset:1024
.LBB0_168:
	s_or_b64 exec, exec, s[6:7]
	buffer_inv sc1
	s_waitcnt vmcnt(0)

; __device__ __forceinline__ unsigned xb_add(unsigned* p, unsigned v) { return __hip_atomic_fetch_add(p, v, __ATOMIC_RELAXED, __HIP_MEMORY_SCOPE_AGENT); }
; __device__ __forceinline__ void grid_barrier(unsigned* bar, unsigned G, int tid, volatile LAS unsigned* st) {
;     ...
;             __builtin_amdgcn_fence(__ATOMIC_ACQUIRE, "agent");
;             xb_add(&bar[XB_XGEN(x)], 1u);
;             asm volatile("s_waitcnt vmcnt(0)" ::: "memory");
.LBB0_379:
	s_or_b64 exec, exec, s[2:3]
	s_mov_b64 s[2:3], exec
	v_mbcnt_lo_u32_b32 v0, s2, 0
	v_mbcnt_hi_u32_b32 v0, s3, v0
	v_cmp_eq_u32_e32 vcc, 0, v0
	s_waitcnt vmcnt(0)
	s_and_saveexec_b64 s[6:7], vcc
	s_cbranch_execz .LBB0_381
	s_bcnt1_i32_b64 s2, s[2:3]
	v_mov_b32_e32 v0, 0x2000
	v_mov_b32_e32 v1, s2
	global_atomic_add v0, v1, s[4:5] offset:1024

; __device__ __forceinline__ unsigned xb_add(unsigned* p, unsigned v) { return __hip_atomic_fetch_add(p, v, __ATOMIC_RELAXED, __HIP_MEMORY_SCOPE_AGENT); }
; __device__ __forceinline__ void grid_barrier(unsigned* bar, unsigned G, int tid, volatile LAS unsigned* st) {
;     ...
;             __builtin_amdgcn_fence(__ATOMIC_ACQUIRE, "agent");
;             xb_add(&bar[XB_XGEN(x)], 1u);
;             asm volatile("s_waitcnt vmcnt(0)" ::: "memory");
.LBB0_906:
	s_or_b64 exec, exec, s[4:5]
	s_mov_b64 s[4:5], exec
	v_mbcnt_lo_u32_b32 v0, s4, 0
	v_mbcnt_hi_u32_b32 v0, s5, v0
	v_cmp_eq_u32_e32 vcc, 0, v0
	s_waitcnt vmcnt(0)
	s_and_saveexec_b64 s[6:7], vcc
	s_cbranch_execz .LBB0_908
	s_bcnt1_i32_b64 s4, s[4:5]
	v_mov_b32_e32 v0, s4
	global_atomic_add v199, v0, s[2:3] offset:1024

; __device__ __forceinline__ unsigned xb_add(unsigned* p, unsigned v) { return __hip_atomic_fetch_add(p, v, __ATOMIC_RELAXED, __HIP_MEMORY_SCOPE_AGENT); }
; __device__ __forceinline__ void grid_barrier(unsigned* bar, unsigned G, int tid, volatile LAS unsigned* st) {
;     ...
;             __builtin_amdgcn_fence(__ATOMIC_ACQUIRE, "agent");
;             xb_add(&bar[XB_XGEN(x)], 1u);
;             asm volatile("s_waitcnt vmcnt(0)" ::: "memory");
.LBB0_1402:
	s_or_b64 exec, exec, s[2:3]
	s_mov_b64 s[2:3], exec
	v_mbcnt_lo_u32_b32 v0, s2, 0
	v_mbcnt_hi_u32_b32 v0, s3, v0
	v_cmp_eq_u32_e32 vcc, 0, v0
	s_waitcnt vmcnt(0)
	s_and_saveexec_b64 s[6:7], vcc
	s_cbranch_execz .LBB0_1404
	s_bcnt1_i32_b64 s2, s[2:3]
	v_mov_b32_e32 v0, s2
	global_atomic_add v199, v0, s[4:5] offset:1024

; __device__ __forceinline__ unsigned xb_add(unsigned* p, unsigned v) { return __hip_atomic_fetch_add(p, v, __ATOMIC_RELAXED, __HIP_MEMORY_SCOPE_AGENT); }
; __device__ __forceinline__ void grid_barrier(unsigned* bar, unsigned G, int tid, volatile LAS unsigned* st) {
;     ...
;             __builtin_amdgcn_fence(__ATOMIC_ACQUIRE, "agent");
;             xb_add(&bar[XB_XGEN(x)], 1u);
;             asm volatile("s_waitcnt vmcnt(0)" ::: "memory");
.LBB0_2154:
	s_or_b64 exec, exec, s[2:3]
	s_mov_b64 s[2:3], exec
	v_mbcnt_lo_u32_b32 v0, s2, 0
	v_mbcnt_hi_u32_b32 v0, s3, v0
	v_cmp_eq_u32_e32 vcc, 0, v0
	s_waitcnt vmcnt(0)
	s_and_saveexec_b64 s[6:7], vcc
	s_cbranch_execnz .LBB0_2155
	buffer_inv sc1
	s_getpc_b64 s[98:99]

; __device__ __forceinline__ unsigned xb_add(unsigned* p, unsigned v) { return __hip_atomic_fetch_add(p, v, __ATOMIC_RELAXED, __HIP_MEMORY_SCOPE_AGENT); }
; __device__ __forceinline__ void grid_barrier(unsigned* bar, unsigned G, int tid, volatile LAS unsigned* st) {
;     ...
;             __builtin_amdgcn_fence(__ATOMIC_ACQUIRE, "agent");
;             xb_add(&bar[XB_XGEN(x)], 1u);
;             asm volatile("s_waitcnt vmcnt(0)" ::: "memory");
.LBB0_2155:
	s_bcnt1_i32_b64 s2, s[2:3]
	v_mov_b32_e32 v0, s2
	global_atomic_add v199, v0, s[4:5] offset:1024
	buffer_inv sc1
	s_getpc_b64 s[98:99]
